# v18 + rw_gemm2 epilogue: the three later bias loads issued with the first one (no per-column-group wait)
# speedup vs baseline: 1.0099x; 1.0039x over previous
.LBB0_648:
	s_and_b32 s0, s10, 7
	s_mulk_i32 s0, 0x210
	s_ashr_i32 s1, s10, 3
	s_add_i32 s11, s0, s1
	s_mul_hi_i32 s0, s11, 0x3e0f83e1
	s_lshr_b32 s1, s0, 31
	s_ashr_i32 s0, s0, 8
	s_add_i32 s20, s0, s1
	s_mul_i32 s0, s20, 0x420
	s_sub_i32 s1, s11, s0
	s_lshl_b32 s0, s1, 4
	s_and_b32 s0, s0, 0xffffff80
	s_lshl_b32 s1, s1, 7
	s_and_b32 s18, s1, 0x380
	s_ashr_i32 s1, s0, 31
	s_lshl_b64 s[8:9], s[0:1], 9
	v_readlane_b32 s12, v182, 27
	v_readlane_b32 s13, v182, 28
	s_add_u32 s1, s12, s8
	s_addc_u32 s12, s13, s9
	s_lshl_b32 s8, s20, 6
	s_ashr_i32 s9, s8, 31
	s_lshl_b64 s[8:9], s[8:9], 1
	s_add_u32 s8, s1, s8
	s_addc_u32 s9, s12, s9
	s_ashr_i32 s21, s20, 31
	s_lshl_b64 s[12:13], s[20:21], 17
	v_readlane_b32 s1, v183, 55
	s_add_u32 s1, s1, s12
	v_readlane_b32 s12, v183, 56
	s_addc_u32 s13, s12, s13
	s_lshl_b32 s12, s18, 7
	s_add_u32 s12, s1, s12
	v_lshl_add_u64 v[0:1], s[8:9], 0, v[72:73]
	v_readfirstlane_b32 s1, v92
	v_add_u32_e32 v6, 0x1000, v92
	v_lshl_add_u64 v[0:1], v[0:1], 0, v[68:69]
	s_mov_b32 m0, s1
	s_mov_b64 s[8:9], 0x4000
	v_readfirstlane_b32 s1, v6
	v_add_u32_e32 v6, 0x2000, v92
	global_load_lds_dwordx4 v[0:1], off
	v_lshl_add_u64 v[4:5], v[0:1], 0, s[8:9]
	s_mov_b32 m0, s1
	s_mov_b64 s[8:9], 0x8000
	v_readfirstlane_b32 s1, v6
	global_load_lds_dwordx4 v[4:5], off
	v_lshl_add_u64 v[4:5], v[0:1], 0, s[8:9]
	s_mov_b32 m0, s1
	s_mov_b64 s[8:9], 0xc000
	global_load_lds_dwordx4 v[4:5], off
	v_add_u32_e32 v4, 0x3000, v92
	v_lshl_add_u64 v[0:1], v[0:1], 0, s[8:9]
	v_readfirstlane_b32 s1, v4
	s_mov_b32 m0, s1
	s_addc_u32 s13, s13, 0
	global_load_lds_dwordx4 v[0:1], off
	v_add_u32_e32 v0, 0x8000, v92
	v_lshl_add_u64 v[2:3], s[12:13], 0, v[74:75]
	v_readfirstlane_b32 s1, v0
	v_add_u32_e32 v4, 0x9000, v92
	v_lshl_add_u64 v[2:3], v[2:3], 0, v[68:69]
	s_mov_b32 m0, s1
	s_mov_b64 s[8:9], 0x1000
	v_readfirstlane_b32 s1, v4
	v_add_u32_e32 v4, 0xa000, v92
	global_load_lds_dwordx4 v[2:3], off
	v_lshl_add_u64 v[0:1], v[2:3], 0, s[8:9]
	s_mov_b32 m0, s1
	s_mov_b64 s[8:9], 0x2000
	v_readfirstlane_b32 s1, v4
	global_load_lds_dwordx4 v[0:1], off
	v_lshl_add_u64 v[0:1], v[2:3], 0, s[8:9]
	s_mov_b32 m0, s1
	s_mov_b64 s[8:9], 0x3000
	global_load_lds_dwordx4 v[0:1], off
	v_lshl_add_u64 v[0:1], v[2:3], 0, s[8:9]
	v_add_u32_e32 v2, 0xb000, v92
	s_nop 0
	v_readfirstlane_b32 s1, v2
	s_mov_b32 m0, s1
	s_nop 0
	global_load_lds_dwordx4 v[0:1], off
	s_waitcnt vmcnt(0)
	s_waitcnt vmcnt(0) lgkmcnt(0)
	s_barrier
	ds_read_b128 v[0:3], v88
	ds_read_b128 v[4:7], v88 offset:2048
	ds_read_b128 v[8:11], v88 offset:4096
	ds_read_b128 v[12:15], v88 offset:6144
	ds_read_b128 v[16:19], v89 offset:32768
	ds_read_b128 v[20:23], v89 offset:34816
	ds_read_b128 v[24:27], v89 offset:36864
	ds_read_b128 v[28:31], v89 offset:38912
	s_setprio 1
	s_waitcnt lgkmcnt(3)
	v_mfma_f32_16x16x32_bf16 v[32:35], v[16:19], v[0:3], 0
	s_waitcnt lgkmcnt(2)
	v_mfma_f32_16x16x32_bf16 v[36:39], v[20:23], v[0:3], 0
	s_waitcnt lgkmcnt(1)
	v_mfma_f32_16x16x32_bf16 v[40:43], v[24:27], v[0:3], 0
	s_waitcnt lgkmcnt(0)
	v_mfma_f32_16x16x32_bf16 v[0:3], v[28:31], v[0:3], 0
	v_mfma_f32_16x16x32_bf16 v[48:51], v[16:19], v[4:7], 0
	v_mfma_f32_16x16x32_bf16 v[52:55], v[20:23], v[4:7], 0
	v_mfma_f32_16x16x32_bf16 v[56:59], v[24:27], v[4:7], 0
	v_mfma_f32_16x16x32_bf16 v[4:7], v[28:31], v[4:7], 0
	v_mfma_f32_16x16x32_bf16 v[76:79], v[16:19], v[8:11], 0
	v_mfma_f32_16x16x32_bf16 v[80:83], v[20:23], v[8:11], 0
	v_mfma_f32_16x16x32_bf16 v[16:19], v[16:19], v[12:15], 0
	v_mfma_f32_16x16x32_bf16 v[94:97], v[24:27], v[8:11], 0
	v_mfma_f32_16x16x32_bf16 v[98:101], v[28:31], v[8:11], 0
	v_mfma_f32_16x16x32_bf16 v[120:123], v[20:23], v[12:15], 0
	v_mfma_f32_16x16x32_bf16 v[124:127], v[24:27], v[12:15], 0
	v_mfma_f32_16x16x32_bf16 v[128:131], v[28:31], v[12:15], 0
	s_setprio 0
	ds_read_b128 v[8:11], v90
	ds_read_b128 v[20:23], v90 offset:2048
	ds_read_b128 v[132:135], v90 offset:4096
	ds_read_b128 v[136:139], v90 offset:6144
	ds_read_b128 v[140:143], v91 offset:32768
	ds_read_b128 v[144:147], v91 offset:34816
	ds_read_b128 v[148:151], v91 offset:36864
	ds_read_b128 v[152:155], v91 offset:38912
	s_setprio 1
	s_waitcnt lgkmcnt(3)
	v_mfma_f32_16x16x32_bf16 v[156:159], v[140:143], v[8:11], v[32:35]
	s_waitcnt lgkmcnt(2)
	v_mfma_f32_16x16x32_bf16 v[44:47], v[144:147], v[8:11], v[36:39]
	s_waitcnt lgkmcnt(1)
	v_mfma_f32_16x16x32_bf16 v[28:31], v[148:151], v[8:11], v[40:43]
	s_waitcnt lgkmcnt(0)
	v_mfma_f32_16x16x32_bf16 v[12:15], v[152:155], v[8:11], v[0:3]
	v_mfma_f32_16x16x32_bf16 v[60:63], v[140:143], v[20:23], v[48:51]
	v_mfma_f32_16x16x32_bf16 v[40:43], v[144:147], v[20:23], v[52:55]
	v_mfma_f32_16x16x32_bf16 v[24:27], v[148:151], v[20:23], v[56:59]
	v_mfma_f32_16x16x32_bf16 v[8:11], v[152:155], v[20:23], v[4:7]
	v_mfma_f32_16x16x32_bf16 v[56:59], v[140:143], v[132:135], v[76:79]
	v_mfma_f32_16x16x32_bf16 v[36:39], v[144:147], v[132:135], v[80:83]
	v_mfma_f32_16x16x32_bf16 v[20:23], v[148:151], v[132:135], v[94:97]
	v_mfma_f32_16x16x32_bf16 v[4:7], v[152:155], v[132:135], v[98:101]
	v_mfma_f32_16x16x32_bf16 v[48:51], v[140:143], v[136:139], v[16:19]
	v_mfma_f32_16x16x32_bf16 v[32:35], v[144:147], v[136:139], v[120:123]
	v_mfma_f32_16x16x32_bf16 v[16:19], v[148:151], v[136:139], v[124:127]
	v_mfma_f32_16x16x32_bf16 v[0:3], v[152:155], v[136:139], v[128:131]
	s_setprio 0
	s_and_b32 s1, s20, 1
	s_cmpk_gt_i32 s11, 0x83f
	s_cselect_b64 s[24:25], -1, 0
	s_cmpk_lt_i32 s11, 0x840
	s_cselect_b64 s[36:37], -1, 0
	v_readlane_b32 s40, v183, 35
	s_and_b64 s[8:9], s[36:37], exec
	v_readlane_b32 s44, v183, 39
	v_readlane_b32 s45, v183, 40
	v_readlane_b32 s50, v183, 45
	v_readlane_b32 s51, v183, 46
	s_cselect_b32 s8, s45, s51
	s_cselect_b32 s9, s44, s50
	s_lshl_b32 s11, s1, 12
	s_add_u32 s20, s9, s11
	v_or_b32_e32 v79, s18, v87
	s_addc_u32 s21, s8, 0
	v_lshlrev_b32_e32 v78, 2, v79
	s_waitcnt vmcnt(0)
	s_barrier
	global_load_dwordx4 v[52:55], v78, s[20:21]
	global_load_dwordx4 v[184:187], v78, s[20:21] offset:64
	global_load_dwordx4 v[188:191], v78, s[20:21] offset:128
	global_load_dwordx4 v[192:195], v78, s[20:21] offset:192
	s_mov_b64 s[8:9], -1
	s_and_b64 vcc, exec, s[24:25]
	v_readlane_b32 s41, v183, 36
	v_readlane_b32 s42, v183, 37
	v_readlane_b32 s43, v183, 38
	v_readlane_b32 s46, v183, 41
	v_readlane_b32 s47, v183, 42
	v_readlane_b32 s48, v183, 43
	v_readlane_b32 s49, v183, 44
	v_readlane_b32 s52, v183, 47
	v_readlane_b32 s53, v183, 48
	v_readlane_b32 s54, v183, 49
	v_readlane_b32 s55, v183, 50
	s_waitcnt vmcnt(0)
	v_add_f32_e32 v76, v156, v52
	v_mul_f32_e32 v76, 0xbfb8aa3b, v76
	v_exp_f32_e32 v76, v76
	v_add_f32_e32 v77, v157, v53
	v_add_f32_e32 v80, v158, v54
	v_add_f32_e32 v81, v159, v55
	v_mul_f32_e32 v77, 0xbfb8aa3b, v77
	v_mul_f32_e32 v80, 0xbfb8aa3b, v80
	v_mul_f32_e32 v83, 0xbfb8aa3b, v81
	v_add_f32_e32 v76, 1.0, v76
	v_exp_f32_e32 v82, v77
	v_exp_f32_e32 v81, v80
	v_rcp_f32_e32 v76, v76
	v_exp_f32_e32 v80, v83
	s_cbranch_vccz .LBB0_650
	v_add_f32_e32 v77, 1.0, v82
	v_rcp_f32_e32 v84, v77
	v_add_f32_e32 v77, 1.0, v81
	v_rcp_f32_e32 v85, v77
	v_add_f32_e32 v77, 1.0, v80
	v_rcp_f32_e32 v77, v77
	s_mov_b64 s[8:9], 0

.LBB0_664:
	s_nop 0
	v_cvt_pk_bf16_f32 v48, v48, v50
	v_or_b32_e32 v50, 48, v82
	v_cvt_pk_bf16_f32 v49, v51, v49
	v_ashrrev_i32_e32 v51, 31, v50
	v_lshlrev_b64 v[50:51], 11, v[50:51]
	v_mov_b32_e32 v79, v69
	v_lshl_add_u64 v[52:53], v[80:81], 0, v[50:51]
	v_lshl_add_u64 v[54:55], s[20:21], 0, v[78:79]
	global_store_dwordx2 v[52:53], v[48:49], off
	v_mov_b32_e32 v48, v184
	v_mov_b32_e32 v49, v185
	v_mov_b32_e32 v50, v186
	v_mov_b32_e32 v51, v187
	s_and_b64 vcc, exec, s[36:37]
	s_mov_b64 s[0:1], -1
	v_add_f32_e32 v44, v44, v48
	v_mul_f32_e32 v44, 0xbfb8aa3b, v44
	v_exp_f32_e32 v44, v44
	v_add_f32_e32 v45, v45, v49
	v_add_f32_e32 v46, v46, v50
	v_add_f32_e32 v47, v47, v51
	v_mul_f32_e32 v45, 0xbfb8aa3b, v45
	v_mul_f32_e32 v46, 0xbfb8aa3b, v46
	v_mul_f32_e32 v47, 0xbfb8aa3b, v47
	v_add_f32_e32 v44, 1.0, v44
	v_exp_f32_e32 v62, v45
	v_exp_f32_e32 v59, v46
	v_rcp_f32_e32 v44, v44
	v_exp_f32_e32 v58, v47
	s_cbranch_vccnz .LBB0_666
	v_add_f32_e32 v45, 1.0, v62
	v_rcp_f32_e32 v46, v45
	v_add_f32_e32 v45, 1.0, v59
	v_rcp_f32_e32 v47, v45
	v_add_f32_e32 v45, 1.0, v58
	v_rcp_f32_e32 v45, v45
	s_mov_b64 s[0:1], 0

.LBB0_680:
	s_nop 0
	v_cvt_pk_bf16_f32 v32, v32, v34
	v_cvt_pk_bf16_f32 v33, v35, v33
	global_store_dwordx2 v[52:53], v[32:33], off offset:32
	v_mov_b32_e32 v32, v188
	v_mov_b32_e32 v33, v189
	v_mov_b32_e32 v34, v190
	v_mov_b32_e32 v35, v191
	s_and_b64 vcc, exec, s[36:37]
	s_mov_b64 s[0:1], -1
	v_add_f32_e32 v28, v28, v32
	v_mul_f32_e32 v28, 0xbfb8aa3b, v28
	v_exp_f32_e32 v28, v28
	v_add_f32_e32 v29, v29, v33
	v_add_f32_e32 v30, v30, v34
	v_add_f32_e32 v31, v31, v35
	v_mul_f32_e32 v29, 0xbfb8aa3b, v29
	v_mul_f32_e32 v30, 0xbfb8aa3b, v30
	v_mul_f32_e32 v31, 0xbfb8aa3b, v31
	v_add_f32_e32 v28, 1.0, v28
	v_exp_f32_e32 v38, v29
	v_exp_f32_e32 v37, v30
	v_rcp_f32_e32 v28, v28
	v_exp_f32_e32 v36, v31
	s_cbranch_vccnz .LBB0_682
	v_add_f32_e32 v29, 1.0, v38
	v_rcp_f32_e32 v30, v29
	v_add_f32_e32 v29, 1.0, v37
	v_rcp_f32_e32 v31, v29
	v_add_f32_e32 v29, 1.0, v36
	v_rcp_f32_e32 v29, v29
	s_mov_b64 s[0:1], 0

.LBB0_696:
	s_nop 0
	v_cvt_pk_bf16_f32 v16, v16, v18
	v_cvt_pk_bf16_f32 v17, v19, v17
	global_store_dwordx2 v[52:53], v[16:17], off offset:64
	v_mov_b32_e32 v16, v192
	v_mov_b32_e32 v17, v193
	v_mov_b32_e32 v18, v194
	v_mov_b32_e32 v19, v195
	s_and_b64 vcc, exec, s[36:37]
	s_mov_b64 s[0:1], -1
	v_add_f32_e32 v12, v12, v16
	v_mul_f32_e32 v12, 0xbfb8aa3b, v12
	v_exp_f32_e32 v12, v12
	v_add_f32_e32 v13, v13, v17
	v_add_f32_e32 v14, v14, v18
	v_add_f32_e32 v15, v15, v19
	v_mul_f32_e32 v13, 0xbfb8aa3b, v13
	v_mul_f32_e32 v14, 0xbfb8aa3b, v14
	v_mul_f32_e32 v15, 0xbfb8aa3b, v15
	v_add_f32_e32 v12, 1.0, v12
	v_exp_f32_e32 v22, v13
	v_exp_f32_e32 v21, v14
	v_rcp_f32_e32 v12, v12
	v_exp_f32_e32 v20, v15
	s_cbranch_vccnz .LBB0_698
	v_add_f32_e32 v13, 1.0, v22
	v_rcp_f32_e32 v14, v13
	v_add_f32_e32 v13, 1.0, v21
	v_rcp_f32_e32 v15, v13
	v_add_f32_e32 v13, 1.0, v20
	v_rcp_f32_e32 v13, v13
	s_mov_b64 s[0:1], 0
